# attention A loop (d)/(e) gaps: row-sum adds placed before the two exps in each MFMA gap
# baseline (speedup 1.0000x reference)
; #define FA_SB() __builtin_amdgcn_sched_barrier(0)
; #define FA_EXP2(J, PX, R) do { const float e0_ = __builtin_amdgcn_exp2f(PX[R]), e1_ = __builtin_amdgcn_exp2f(PX[(R) + 1]); ps += e0_; ps += e1_; PWN[(J) >> 2][(J) & 3] = cvtpk(e0_, e1_); } while (0)
; __device__ __forceinline__ void attn_unit_a(FLAS unsigned char* lds, const Unit u) {
;     ...
;         FA_BIAS(inx, pN0, pN1, cbN, ziN);
;         FA_SB();
;         if (ziN) { pN0 = __builtin_amdgcn_mfma_f32_32x32x16_bf16(kf[0], qr[0], z16, 0, 0, 0); FA_EXP2(8, pC1, 0); FA_SB(); pN1 = __builtin_amdgcn_mfma_f32_32x32x16_bf16(kf[1], qr[0], z16, 0, 0, 0); }
;         else { pN0 = __builtin_amdgcn_mfma_f32_32x32x16_bf16(kf[0], qr[0], pN0, 0, 0, 0); FA_EXP2(8, pC1, 0); FA_SB(); pN1 = __builtin_amdgcn_mfma_f32_32x32x16_bf16(kf[1], qr[0], pN1, 0, 0, 0); }
.Lgather_e:
	v_add_u32_e32 v76, s49, v210
	v_add_u32_e32 v64, 0x17600, v76
	v_add_u32_e32 v66, 0x17680, v76
	v_add_u32_e32 v67, 0x17608, v76
	v_add_u32_e32 v68, 0x17688, v76
	ds_read2_b32 v[64:65], v64 offset1:1
	ds_read2_b32 v[80:81], v66 offset1:1
	ds_read2_b32 v[66:67], v67 offset1:1
	ds_read2_b32 v[82:83], v68 offset1:1
	v_add_u32_e32 v68, 0x17620, v76
	v_add_u32_e32 v70, 0x176a0, v76
	v_add_u32_e32 v71, 0x17628, v76
	v_add_u32_e32 v72, 0x176a8, v76
	ds_read2_b32 v[68:69], v68 offset1:1
	ds_read2_b32 v[84:85], v70 offset1:1
	ds_read2_b32 v[70:71], v71 offset1:1
	ds_read2_b32 v[86:87], v72 offset1:1
	v_add_u32_e32 v72, 0x17640, v76
	v_add_u32_e32 v74, 0x176c0, v76
	v_add_u32_e32 v75, 0x17648, v76
	v_add_u32_e32 v77, 0x176c8, v76
	ds_read2_b32 v[72:73], v72 offset1:1
	ds_read2_b32 v[88:89], v74 offset1:1
	ds_read2_b32 v[74:75], v75 offset1:1
	ds_read2_b32 v[90:91], v77 offset1:1
	v_add_u32_e32 v77, 0x17660, v76
	v_add_u32_e32 v78, 0x176e0, v76
	v_add_u32_e32 v79, 0x17668, v76
	v_add_u32_e32 v94, 0x176e8, v76
	ds_read2_b32 v[76:77], v77 offset1:1
	ds_read2_b32 v[92:93], v78 offset1:1
	ds_read2_b32 v[78:79], v79 offset1:1
	ds_read2_b32 v[94:95], v94 offset1:1
	s_waitcnt lgkmcnt(0)
	v_sub_f32_e32 v64, v64, v211
	v_sub_f32_e32 v65, v65, v211
	v_sub_f32_e32 v66, v66, v211
	v_sub_f32_e32 v67, v67, v211
	v_sub_f32_e32 v68, v68, v211
	v_sub_f32_e32 v69, v69, v211
	v_sub_f32_e32 v70, v70, v211
	v_sub_f32_e32 v71, v71, v211
	v_sub_f32_e32 v72, v72, v211
	v_sub_f32_e32 v73, v73, v211
	v_sub_f32_e32 v74, v74, v211
	v_sub_f32_e32 v75, v75, v211
	v_sub_f32_e32 v76, v76, v211
	v_sub_f32_e32 v77, v77, v211
	v_sub_f32_e32 v78, v78, v211
	v_sub_f32_e32 v79, v79, v211
	v_sub_f32_e32 v80, v80, v211
	v_sub_f32_e32 v81, v81, v211
	v_sub_f32_e32 v82, v82, v211
	v_sub_f32_e32 v83, v83, v211
	v_sub_f32_e32 v84, v84, v211
	v_sub_f32_e32 v85, v85, v211
	v_sub_f32_e32 v86, v86, v211
	v_sub_f32_e32 v87, v87, v211
	v_sub_f32_e32 v88, v88, v211
	v_sub_f32_e32 v89, v89, v211
	v_sub_f32_e32 v90, v90, v211
	v_sub_f32_e32 v91, v91, v211
	v_sub_f32_e32 v92, v92, v211
	v_sub_f32_e32 v93, v93, v211
	v_sub_f32_e32 v94, v94, v211
	v_sub_f32_e32 v95, v95, v211
	s_nop 1
	v_mfma_f32_32x32x16_bf16 v[64:79], v[204:207], v[160:163], v[64:79]
	v_add_f32_e32 v212, v110, v212
	v_add_f32_e32 v212, v111, v212
	v_exp_f32_e32 v112, v112
	v_exp_f32_e32 v113, v113
	v_mfma_f32_32x32x16_bf16 v[80:95], v[200:203], v[160:163], v[80:95]
	v_exp_f32_e32 v114, v114
	v_exp_f32_e32 v115, v115
	s_branch .Lk2_e

; #define FA_SB() __builtin_amdgcn_sched_barrier(0)
; #define FA_EXP2(J, PX, R) do { const float e0_ = __builtin_amdgcn_exp2f(PX[R]), e1_ = __builtin_amdgcn_exp2f(PX[(R) + 1]); ps += e0_; ps += e1_; PWN[(J) >> 2][(J) & 3] = cvtpk(e0_, e1_); } while (0)
; __device__ __forceinline__ void attn_unit_a(FLAS unsigned char* lds, const Unit u) {
;     ...
;         FA_BIAS(inx, pN0, pN1, cbN, ziN);
;         FA_SB();
;         if (ziN) { pN0 = __builtin_amdgcn_mfma_f32_32x32x16_bf16(kf[0], qr[0], z16, 0, 0, 0); FA_EXP2(8, pC1, 0); FA_SB(); pN1 = __builtin_amdgcn_mfma_f32_32x32x16_bf16(kf[1], qr[0], z16, 0, 0, 0); }
;         else { pN0 = __builtin_amdgcn_mfma_f32_32x32x16_bf16(kf[0], qr[0], pN0, 0, 0, 0); FA_EXP2(8, pC1, 0); FA_SB(); pN1 = __builtin_amdgcn_mfma_f32_32x32x16_bf16(kf[1], qr[0], pN1, 0, 0, 0); }
.Lgather_o:
	v_sub_u32_e32 v96, s12, v244
	v_lshl_add_u32 v108, v96, 2, v240
	v_add_u32_e32 v96, 0x1500, v108
	v_add_u32_e32 v98, 0x1580, v108
	v_add_u32_e32 v99, 0x1508, v108
	v_add_u32_e32 v100, 0x1588, v108
	ds_read2_b32 v[96:97], v96 offset1:1
	ds_read2_b32 v[112:113], v98 offset1:1
	ds_read2_b32 v[98:99], v99 offset1:1
	ds_read2_b32 v[114:115], v100 offset1:1
	v_add_u32_e32 v100, 0x1520, v108
	v_add_u32_e32 v102, 0x15a0, v108
	v_add_u32_e32 v103, 0x1528, v108
	v_add_u32_e32 v104, 0x15a8, v108
	ds_read2_b32 v[100:101], v100 offset1:1
	ds_read2_b32 v[116:117], v102 offset1:1
	ds_read2_b32 v[102:103], v103 offset1:1
	ds_read2_b32 v[118:119], v104 offset1:1
	v_add_u32_e32 v104, 0x1540, v108
	v_add_u32_e32 v106, 0x15c0, v108
	v_add_u32_e32 v107, 0x1548, v108
	v_add_u32_e32 v109, 0x15c8, v108
	ds_read2_b32 v[104:105], v104 offset1:1
	ds_read2_b32 v[120:121], v106 offset1:1
	ds_read2_b32 v[106:107], v107 offset1:1
	ds_read2_b32 v[122:123], v109 offset1:1
	v_add_u32_e32 v109, 0x1560, v108
	v_add_u32_e32 v110, 0x15e0, v108
	v_add_u32_e32 v111, 0x1568, v108
	v_add_u32_e32 v126, 0x15e8, v108
	ds_read2_b32 v[108:109], v109 offset1:1
	ds_read2_b32 v[124:125], v110 offset1:1
	ds_read2_b32 v[110:111], v111 offset1:1
	ds_read2_b32 v[126:127], v126 offset1:1
	s_waitcnt lgkmcnt(0)
	v_sub_f32_e32 v96, v96, v211
	v_sub_f32_e32 v97, v97, v211
	v_sub_f32_e32 v98, v98, v211
	v_sub_f32_e32 v99, v99, v211
	v_sub_f32_e32 v100, v100, v211
	v_sub_f32_e32 v101, v101, v211
	v_sub_f32_e32 v102, v102, v211
	v_sub_f32_e32 v103, v103, v211
	v_sub_f32_e32 v104, v104, v211
	v_sub_f32_e32 v105, v105, v211
	v_sub_f32_e32 v106, v106, v211
	v_sub_f32_e32 v107, v107, v211
	v_sub_f32_e32 v108, v108, v211
	v_sub_f32_e32 v109, v109, v211
	v_sub_f32_e32 v110, v110, v211
	v_sub_f32_e32 v111, v111, v211
	v_sub_f32_e32 v112, v112, v211
	v_sub_f32_e32 v113, v113, v211
	v_sub_f32_e32 v114, v114, v211
	v_sub_f32_e32 v115, v115, v211
	v_sub_f32_e32 v116, v116, v211
	v_sub_f32_e32 v117, v117, v211
	v_sub_f32_e32 v118, v118, v211
	v_sub_f32_e32 v119, v119, v211
	v_sub_f32_e32 v120, v120, v211
	v_sub_f32_e32 v121, v121, v211
	v_sub_f32_e32 v122, v122, v211
	v_sub_f32_e32 v123, v123, v211
	v_sub_f32_e32 v124, v124, v211
	v_sub_f32_e32 v125, v125, v211
	v_sub_f32_e32 v126, v126, v211
	v_sub_f32_e32 v127, v127, v211
	s_nop 1
	v_mfma_f32_32x32x16_bf16 v[96:111], v[200:203], v[160:163], v[96:111]
	v_add_f32_e32 v212, v78, v212
	v_add_f32_e32 v212, v79, v212
	v_exp_f32_e32 v80, v80
	v_exp_f32_e32 v81, v81
	v_mfma_f32_32x32x16_bf16 v[112:127], v[196:199], v[160:163], v[112:127]
	v_exp_f32_e32 v82, v82
	v_exp_f32_e32 v83, v83
	s_branch .Lk2_o

; #define FA_SB() __builtin_amdgcn_sched_barrier(0)
; #define FA_PVM(G) do { o[(G) & 3] = __builtin_amdgcn_mfma_f32_32x32x16_bf16(__builtin_bit_cast(bf16x8, vr[(G) % 3]), __builtin_bit_cast(bf16x8, PWC[(G) >> 2]), o[(G) & 3], 0, 0, 0); if ((G) + 3 < 16) vr[(G) % 3] = FA_VFRAG((G) + 3); } while (0)
; #define FA_EXP2(J, PX, R) do { const float e0_ = __builtin_amdgcn_exp2f(PX[R]), e1_ = __builtin_amdgcn_exp2f(PX[(R) + 1]); ps += e0_; ps += e1_; PWN[(J) >> 2][(J) & 3] = cvtpk(e0_, e1_); } while (0)
; __device__ __forceinline__ void attn_unit_a(FLAS unsigned char* lds, const Unit u) {
;     ...
;         for (int g = 8; g < 16; ++g) { FA_PVM(g); FA_EXP2(g - 8, pC0, 2 * (g - 8));
;             if (g == 12) { kf[0] = FA_KF(0, 0); kf[1] = FA_KF(0, 1); kf[2] = FA_KF(1, 0); kf[3] = FA_KF(1, 1); }
;             FA_SB(); }
;         float cbN; bool ziN; const int inx = (i + 1 < NT) ? i + 1 : NT - 1;
;         FA_BIAS(inx, pN0, pN1, cbN, ziN);
;         FA_SB();
;         if (ziN) { pN0 = __builtin_amdgcn_mfma_f32_32x32x16_bf16(kf[0], qr[0], z16, 0, 0, 0); FA_EXP2(8, pC1, 0); FA_SB(); pN1 = __builtin_amdgcn_mfma_f32_32x32x16_bf16(kf[1], qr[0], z16, 0, 0, 0); }
;         else { pN0 = __builtin_amdgcn_mfma_f32_32x32x16_bf16(kf[0], qr[0], pN0, 0, 0, 0); FA_EXP2(8, pC1, 0); FA_SB(); pN1 = __builtin_amdgcn_mfma_f32_32x32x16_bf16(kf[1], qr[0], pN1, 0, 0, 0); }
.LBB0_442:
	s_waitcnt lgkmcnt(1)
	v_mfma_f32_32x32x16_bf16 v[48:63], v[136:139], v[192:195], v[48:63]
	ds_read_b128 v[136:139], v200 offset:30272
	v_exp_f32_e32 v96, v96
	v_exp_f32_e32 v97, v97
	v_mfma_f32_32x32x16_bf16 v[32:47], v[128:131], v[192:195], v[32:47]
	ds_read_b128 v[128:131], v200 offset:16480
	v_add_f32_e32 v212, v96, v212
	v_add_f32_e32 v212, v97, v212
	v_exp_f32_e32 v98, v98
	v_exp_f32_e32 v99, v99
	s_waitcnt lgkmcnt(1)
	v_mfma_f32_32x32x16_bf16 v[16:31], v[132:135], v[192:195], v[16:31]
	ds_read_b128 v[132:135], v200 offset:21088
	v_add_f32_e32 v212, v98, v212
	v_add_f32_e32 v212, v99, v212
	v_exp_f32_e32 v100, v100
	v_exp_f32_e32 v101, v101
	v_mfma_f32_32x32x16_bf16 v[0:15], v[136:139], v[192:195], v[0:15]
	ds_read_b128 v[136:139], v200 offset:25696
	v_add_f32_e32 v212, v100, v212
	v_add_f32_e32 v212, v101, v212
	v_exp_f32_e32 v102, v102
	v_exp_f32_e32 v103, v103
	s_waitcnt lgkmcnt(1)
	v_mfma_f32_32x32x16_bf16 v[48:63], v[128:131], v[188:191], v[48:63]
	ds_read_b128 v[128:131], v200 offset:30304
	ds_read_b128 v[204:207], v247 offset:8192
	ds_read_b128 v[200:203], v247 offset:8704
	ds_read_b128 v[196:199], v248 offset:8192
	ds_read_b128 v[192:195], v248 offset:8704
	v_add_f32_e32 v212, v102, v212
	v_add_f32_e32 v212, v103, v212
	v_exp_f32_e32 v104, v104
	v_exp_f32_e32 v105, v105
	v_mfma_f32_32x32x16_bf16 v[32:47], v[132:135], v[188:191], v[32:47]
	v_add_f32_e32 v212, v104, v212
	v_add_f32_e32 v212, v105, v212
	v_exp_f32_e32 v106, v106
	v_exp_f32_e32 v107, v107
	s_waitcnt lgkmcnt(4)
	v_mfma_f32_32x32x16_bf16 v[16:31], v[136:139], v[188:191], v[16:31]
	v_add_f32_e32 v212, v106, v212
	v_add_f32_e32 v212, v107, v212
	v_exp_f32_e32 v108, v108
	v_exp_f32_e32 v109, v109
	v_mfma_f32_32x32x16_bf16 v[0:15], v[128:131], v[188:191], v[0:15]
	v_add_f32_e32 v212, v108, v212
	v_add_f32_e32 v212, v109, v212
	v_exp_f32_e32 v110, v110
	v_exp_f32_e32 v111, v111
	s_sub_i32 s12, s48, 31
	s_cmpk_lt_i32 s12, 0x22f
	s_cselect_b32 s98, s100, s101
	s_cselect_b32 s15, 1, 0
	s_cmpk_gt_i32 s48, 0xfd92
	s_cselect_b32 s15, s15, 0
	s_cmp_lg_u32 s15, 0
	s_cbranch_scc1 .Lgather_e
	s_cmp_lg_u32 s99, s98
	s_cbranch_scc1 .Lz_upd_e
.Lz_go_e:
	s_waitcnt lgkmcnt(0)
	v_mfma_f32_32x32x16_bf16 v[64:79], v[204:207], v[160:163], v[144:159]
	v_add_f32_e32 v212, v110, v212
	v_add_f32_e32 v212, v111, v212
	v_exp_f32_e32 v112, v112
	v_exp_f32_e32 v113, v113
	v_mfma_f32_32x32x16_bf16 v[80:95], v[200:203], v[160:163], v[144:159]
	v_exp_f32_e32 v114, v114
	v_exp_f32_e32 v115, v115

; #define FA_SB() __builtin_amdgcn_sched_barrier(0)
; #define FA_PVM(G) do { o[(G) & 3] = __builtin_amdgcn_mfma_f32_32x32x16_bf16(__builtin_bit_cast(bf16x8, vr[(G) % 3]), __builtin_bit_cast(bf16x8, PWC[(G) >> 2]), o[(G) & 3], 0, 0, 0); if ((G) + 3 < 16) vr[(G) % 3] = FA_VFRAG((G) + 3); } while (0)
; #define FA_EXP2(J, PX, R) do { const float e0_ = __builtin_amdgcn_exp2f(PX[R]), e1_ = __builtin_amdgcn_exp2f(PX[(R) + 1]); ps += e0_; ps += e1_; PWN[(J) >> 2][(J) & 3] = cvtpk(e0_, e1_); } while (0)
; __device__ __forceinline__ void attn_unit_a(FLAS unsigned char* lds, const Unit u) {
;     ...
;         for (int g = 8; g < 16; ++g) { FA_PVM(g); FA_EXP2(g - 8, pC0, 2 * (g - 8));
;             if (g == 12) { kf[0] = FA_KF(0, 0); kf[1] = FA_KF(0, 1); kf[2] = FA_KF(1, 0); kf[3] = FA_KF(1, 1); }
;             FA_SB(); }
;         float cbN; bool ziN; const int inx = (i + 1 < NT) ? i + 1 : NT - 1;
;         FA_BIAS(inx, pN0, pN1, cbN, ziN);
;         FA_SB();
;         if (ziN) { pN0 = __builtin_amdgcn_mfma_f32_32x32x16_bf16(kf[0], qr[0], z16, 0, 0, 0); FA_EXP2(8, pC1, 0); FA_SB(); pN1 = __builtin_amdgcn_mfma_f32_32x32x16_bf16(kf[1], qr[0], z16, 0, 0, 0); }
;         else { pN0 = __builtin_amdgcn_mfma_f32_32x32x16_bf16(kf[0], qr[0], pN0, 0, 0, 0); FA_EXP2(8, pC1, 0); FA_SB(); pN1 = __builtin_amdgcn_mfma_f32_32x32x16_bf16(kf[1], qr[0], pN1, 0, 0, 0); }
.LBB0_462:
	s_waitcnt lgkmcnt(1)
	v_mfma_f32_32x32x16_bf16 v[48:63], v[136:139], v[140:143], v[48:63]
	ds_read_b128 v[136:139], v201 offset:30272
	v_exp_f32_e32 v64, v64
	v_exp_f32_e32 v65, v65
	v_cvt_pk_bf16_f32 v232, v120, v121
	v_cvt_pk_bf16_f32 v233, v122, v123
	v_mfma_f32_32x32x16_bf16 v[32:47], v[128:131], v[140:143], v[32:47]
	ds_read_b128 v[128:131], v201 offset:16480
	v_add_f32_e32 v212, v64, v212
	v_add_f32_e32 v212, v65, v212
	v_exp_f32_e32 v66, v66
	v_exp_f32_e32 v67, v67
	v_cvt_pk_bf16_f32 v234, v124, v125
	v_cvt_pk_bf16_f32 v235, v126, v127
	s_waitcnt lgkmcnt(1)
	v_mfma_f32_32x32x16_bf16 v[16:31], v[132:135], v[140:143], v[16:31]
	ds_read_b128 v[132:135], v201 offset:21088
	v_add_f32_e32 v212, v66, v212
	v_add_f32_e32 v212, v67, v212
	v_exp_f32_e32 v68, v68
	v_exp_f32_e32 v69, v69
	v_mfma_f32_32x32x16_bf16 v[0:15], v[136:139], v[140:143], v[0:15]
	ds_read_b128 v[136:139], v201 offset:25696
	v_add_f32_e32 v212, v68, v212
	v_add_f32_e32 v212, v69, v212
	v_exp_f32_e32 v70, v70
	v_exp_f32_e32 v71, v71
	s_waitcnt lgkmcnt(1)
	v_mfma_f32_32x32x16_bf16 v[48:63], v[128:131], v[232:235], v[48:63]
	ds_read_b128 v[128:131], v201 offset:30304
	ds_read_b128 v[200:203], v247
	ds_read_b128 v[196:199], v247 offset:512
	ds_read_b128 v[192:195], v248
	ds_read_b128 v[188:191], v248 offset:512
	v_add_f32_e32 v212, v70, v212
	v_add_f32_e32 v212, v71, v212
	v_exp_f32_e32 v72, v72
	v_exp_f32_e32 v73, v73
	v_mfma_f32_32x32x16_bf16 v[32:47], v[132:135], v[232:235], v[32:47]
	v_add_f32_e32 v212, v72, v212
	v_add_f32_e32 v212, v73, v212
	v_exp_f32_e32 v74, v74
	v_exp_f32_e32 v75, v75
	s_waitcnt lgkmcnt(4)
	v_mfma_f32_32x32x16_bf16 v[16:31], v[136:139], v[232:235], v[16:31]
	v_add_f32_e32 v212, v74, v212
	v_add_f32_e32 v212, v75, v212
	v_exp_f32_e32 v76, v76
	v_exp_f32_e32 v77, v77
	v_mfma_f32_32x32x16_bf16 v[0:15], v[128:131], v[232:235], v[0:15]
	v_add_f32_e32 v212, v76, v212
	v_add_f32_e32 v212, v77, v212
	v_exp_f32_e32 v78, v78
	v_exp_f32_e32 v79, v79
	s_min_u32 s12, s34, 0x7f
	s_lshl_b32 s12, s12, 6
	s_sub_i32 s14, s12, s47
	s_sub_i32 s15, s14, 31
	s_cmpk_lt_i32 s15, 0x22f
	s_cselect_b32 s98, s100, s101
	s_cselect_b32 s15, 1, 0
	s_cmpk_gt_i32 s14, 0xfd92
	s_cselect_b32 s15, s15, 0
	s_cmp_lg_u32 s15, 0
	s_cbranch_scc1 .Lgather_o
	s_cmp_lg_u32 s99, s98
	s_cbranch_scc1 .Lz_upd_o
.Lz_go_o:
	s_waitcnt lgkmcnt(0)
	v_mfma_f32_32x32x16_bf16 v[96:111], v[200:203], v[160:163], v[144:159]
	v_add_f32_e32 v212, v78, v212
	v_add_f32_e32 v212, v79, v212
	v_exp_f32_e32 v80, v80
	v_exp_f32_e32 v81, v81
	v_mfma_f32_32x32x16_bf16 v[112:127], v[196:199], v[160:163], v[144:159]
	v_exp_f32_e32 v82, v82
	v_exp_f32_e32 v83, v83
